# P4 fs_direct: issue per-step weight loads before the row prefetch so in-order vmcnt waits stop draining the HBM row loads
# speedup vs baseline: 1.0032x; 1.0032x over previous
.LBB0_774:
	s_nop 0
	ds_read_b128 v[194:197], v193
	ds_read_b128 v[198:201], v193 offset:1024
	s_waitcnt vmcnt(14)
	v_cvt_pk_bf16_f32 v14, v14, v15
	v_cvt_pk_bf16_f32 v15, v16, v17
	v_cvt_pk_bf16_f32 v16, v10, v11
	v_cvt_pk_bf16_f32 v17, v12, v13
	s_waitcnt vmcnt(10)
	v_cvt_pk_bf16_f32 v10, v30, v31
	v_cvt_pk_bf16_f32 v11, v32, v33
	v_cvt_pk_bf16_f32 v12, v26, v27
	v_cvt_pk_bf16_f32 v13, v28, v29
	s_waitcnt lgkmcnt(1)
	v_mfma_f32_16x16x32_bf16 v[130:133], v[194:197], v[14:17], v[130:133]
	ds_read_b128 v[26:29], v193 offset:2048
	s_cmp_lt_u32 s73, 14
	s_cselect_b64 s[6:7], -1, 0
	v_mfma_f32_16x16x32_bf16 v[114:117], v[194:197], v[10:13], v[114:117]
	v_cvt_pk_bf16_f32 v196, v2, v3
	v_cvt_pk_bf16_f32 v197, v4, v5
	ds_read_b128 v[2:5], v193 offset:3072
	s_waitcnt lgkmcnt(2)
	v_mfma_f32_16x16x32_bf16 v[126:129], v[198:201], v[14:17], v[126:129]
	v_cvt_pk_bf16_f32 v194, v6, v7
	v_cvt_pk_bf16_f32 v195, v8, v9
	s_and_b64 s[6:7], s[6:7], exec
	v_mfma_f32_16x16x32_bf16 v[106:109], v[198:201], v[10:13], v[106:109]
	s_waitcnt vmcnt(8)
	v_cvt_pk_bf16_f32 v198, v22, v23
	v_cvt_pk_bf16_f32 v199, v24, v25
	v_cvt_pk_bf16_f32 v200, v18, v19
	s_waitcnt lgkmcnt(1)
	v_mfma_f32_16x16x32_bf16 v[118:121], v[26:29], v[14:17], v[118:121]
	v_cvt_pk_bf16_f32 v201, v20, v21
	ds_read_b128 v[6:9], v193 offset:4096
	ds_read_b128 v[18:21], v193 offset:5120
	s_cselect_b32 s60, s71, 0x3e0
	v_mfma_f32_16x16x32_bf16 v[102:105], v[26:29], v[10:13], v[102:105]
	ds_read_b128 v[22:25], v193 offset:6144
	ds_read_b128 v[26:29], v193 offset:7168
	s_waitcnt vmcnt(1)
	ds_write_b128 v164, v[66:69] offset:16384
	s_sub_i32 s61, s71, 32
	s_waitcnt lgkmcnt(5)
	v_mfma_f32_16x16x32_bf16 v[110:113], v[2:5], v[14:17], v[110:113]
	s_cmp_lt_u32 s73, 14
	s_waitcnt vmcnt(0)
	ds_write_b128 v192, v[70:73] offset:16384
	s_cselect_b64 s[6:7], -1, 0
	v_mfma_f32_16x16x32_bf16 v[66:69], v[2:5], v[10:13], v[86:89]
	v_lshl_add_u64 v[2:3], v[178:179], 0, v[162:163]
	v_add_co_u32_e32 v214, vcc, s67, v2
	v_lshl_add_u64 v[4:5], v[180:181], 0, v[162:163]
	s_nop 0
	v_addc_co_u32_e32 v215, vcc, 0, v3, vcc
	v_add_co_u32_e32 v216, vcc, s67, v4
	s_waitcnt lgkmcnt(5)
	v_mfma_f32_16x16x32_bf16 v[70:73], v[6:9], v[14:17], v[94:97]
	v_addc_co_u32_e32 v217, vcc, 0, v5, vcc
	s_and_b64 vcc, s[6:7], exec
	s_waitcnt lgkmcnt(4)
	v_mfma_f32_16x16x32_bf16 v[86:89], v[18:21], v[14:17], v[90:93]
	s_cselect_b32 s10, s72, 0x3c00
	s_cselect_b32 s6, s61, 0x3e0
	s_lshl_b64 s[74:75], s[10:11], 2
	v_mfma_f32_16x16x32_bf16 v[90:93], v[18:21], v[10:13], v[98:101]
	global_load_dwordx4 v[94:97], v[214:215], off offset:128
	s_nop 1
	global_load_dwordx4 v[98:101], v[216:217], off offset:128
	global_load_dwordx4 v[234:237], v[214:215], off offset:192
	global_load_dwordx4 v[238:241], v[216:217], off offset:192
	s_waitcnt vmcnt(9)
	v_cvt_pk_bf16_f32 v210, v58, v59
	v_cvt_pk_bf16_f32 v211, v60, v61
	v_mfma_f32_16x16x32_bf16 v[78:81], v[6:9], v[10:13], v[78:81]
	v_lshl_add_u64 v[6:7], v[174:175], 0, s[74:75]
	s_waitcnt vmcnt(8)
	v_cvt_pk_bf16_f32 v212, v62, v63
	v_cvt_pk_bf16_f32 v213, v64, v65
	s_waitcnt lgkmcnt(3)
	v_mfma_f32_16x16x32_bf16 v[74:77], v[22:25], v[14:17], v[74:77]
	s_min_u32 s10, s73, 12
	s_mov_b32 s7, s11
	s_lshl_b32 s10, s10, 12
	v_mfma_f32_16x16x32_bf16 v[82:85], v[22:25], v[10:13], v[82:85]
	v_lshl_add_u64 v[22:23], v[176:177], 0, s[74:75]
	s_lshl_b64 s[6:7], s[6:7], 1
	s_mov_b32 s61, s11
	s_waitcnt lgkmcnt(2)
	v_mfma_f32_16x16x32_bf16 v[202:205], v[26:29], v[14:17], v[122:125]
	v_lshl_add_u64 v[180:181], v[180:181], 0, s[58:59]
	v_lshl_add_u64 v[178:179], v[178:179], 0, s[58:59]
	s_add_i32 s73, s73, 2
	v_mfma_f32_16x16x32_bf16 v[134:137], v[26:29], v[10:13], v[134:137]
	global_load_dwordx4 v[10:13], v[6:7], off offset:16
	global_load_dwordx4 v[14:17], v[6:7], off
	global_load_dwordx4 v[2:5], v[6:7], off offset:144
	s_nop 0
	global_load_dwordx4 v[6:9], v[6:7], off offset:128
	s_nop 0
	global_load_dwordx4 v[26:29], v[22:23], off offset:16
	global_load_dwordx4 v[30:33], v[22:23], off
	global_load_dwordx4 v[18:21], v[22:23], off offset:144
	s_nop 0
	global_load_dwordx4 v[22:25], v[22:23], off offset:128
	s_waitcnt lgkmcnt(0)
	s_barrier
	ds_read_b128 v[122:125], v193 offset:16384
	ds_read_b128 v[206:209], v193 offset:17408
	s_waitcnt lgkmcnt(1)
	v_mfma_f32_16x16x32_bf16 v[130:133], v[122:125], v[194:197], v[130:133]
	s_addk_i32 s71, 0x80
	s_addk_i32 s72, 0x800
	v_mfma_f32_16x16x32_bf16 v[114:117], v[122:125], v[198:201], v[114:117]
	s_waitcnt lgkmcnt(0)
	v_mfma_f32_16x16x32_bf16 v[126:129], v[206:209], v[194:197], v[126:129]
	v_mfma_f32_16x16x32_bf16 v[106:109], v[206:209], v[198:201], v[106:109]
	ds_read_b128 v[122:125], v193 offset:18432
	ds_read_b128 v[206:209], v193 offset:19456
	s_waitcnt lgkmcnt(1)
	v_mfma_f32_16x16x32_bf16 v[118:121], v[122:125], v[194:197], v[118:121]
	v_mfma_f32_16x16x32_bf16 v[102:105], v[122:125], v[198:201], v[102:105]
	s_waitcnt lgkmcnt(0)
	v_mfma_f32_16x16x32_bf16 v[110:113], v[206:209], v[194:197], v[110:113]
	v_mfma_f32_16x16x32_bf16 v[66:69], v[206:209], v[198:201], v[66:69]
	ds_read_b128 v[122:125], v193 offset:20480
	ds_read_b128 v[206:209], v193 offset:21504
	ds_read_b128 v[58:61], v193 offset:22528
	ds_read_b128 v[62:65], v193 offset:23552
	s_waitcnt lgkmcnt(3)
	v_mfma_f32_16x16x32_bf16 v[70:73], v[122:125], v[194:197], v[70:73]
	s_waitcnt lgkmcnt(2)
	v_mfma_f32_16x16x32_bf16 v[86:89], v[206:209], v[194:197], v[86:89]
	s_waitcnt lgkmcnt(1)
	v_mfma_f32_16x16x32_bf16 v[74:77], v[58:61], v[194:197], v[74:77]
	s_waitcnt lgkmcnt(0)
	v_mfma_f32_16x16x32_bf16 v[194:197], v[62:65], v[194:197], v[202:205]
	s_nop 2
	s_nop 0
	s_waitcnt vmcnt(11)
	ds_write_b128 v164, v[94:97]
	s_waitcnt vmcnt(10)
	ds_write_b128 v192, v[98:101]
	v_mfma_f32_16x16x32_bf16 v[78:81], v[122:125], v[198:201], v[78:81]
	s_waitcnt lgkmcnt(0)
	s_barrier
	v_mfma_f32_16x16x32_bf16 v[90:93], v[206:209], v[198:201], v[90:93]
	v_cvt_pk_bf16_f32 v206, v46, v47
	v_cvt_pk_bf16_f32 v207, v48, v49
	v_cvt_pk_bf16_f32 v208, v42, v43
	v_mfma_f32_16x16x32_bf16 v[82:85], v[58:61], v[198:201], v[82:85]
	v_cvt_pk_bf16_f32 v209, v44, v45
	ds_read_b128 v[42:45], v193
	ds_read_b128 v[46:49], v193 offset:1024
	v_cvt_pk_bf16_f32 v122, v54, v55
	v_mfma_f32_16x16x32_bf16 v[134:137], v[62:65], v[198:201], v[134:137]
	v_cvt_pk_bf16_f32 v198, v38, v39
	v_cvt_pk_bf16_f32 v199, v40, v41
	v_cvt_pk_bf16_f32 v200, v34, v35
	v_cvt_pk_bf16_f32 v201, v36, v37
	ds_read_b128 v[34:37], v193 offset:2048
	ds_read_b128 v[38:41], v193 offset:3072
	s_waitcnt lgkmcnt(3)
	v_mfma_f32_16x16x32_bf16 v[94:97], v[42:45], v[210:213], v[130:133]
	v_cvt_pk_bf16_f32 v123, v56, v57
	v_cvt_pk_bf16_f32 v124, v50, v51
	v_cvt_pk_bf16_f32 v125, v52, v53
	v_mfma_f32_16x16x32_bf16 v[98:101], v[42:45], v[206:209], v[114:117]
	v_lshl_add_u64 v[42:43], v[174:175], 0, s[10:11]
	v_lshl_add_u64 v[130:131], v[166:167], 0, s[6:7]
	v_lshl_add_u64 v[132:133], v[168:169], 0, s[6:7]
	global_load_dwordx4 v[242:245], v[130:131], off
	global_load_dwordx4 v[246:249], v[132:133], off
	s_waitcnt lgkmcnt(1)
	v_mfma_f32_16x16x32_bf16 v[118:121], v[34:37], v[210:213], v[118:121]
	v_lshl_add_u64 v[44:45], v[176:177], 0, s[10:11]
	v_lshl_add_u64 v[226:227], v[44:45], 0, s[54:55]
	v_mfma_f32_16x16x32_bf16 v[102:105], v[34:37], v[206:209], v[102:105]
	s_waitcnt lgkmcnt(0)
	v_mfma_f32_16x16x32_bf16 v[110:113], v[38:41], v[210:213], v[110:113]
	v_mfma_f32_16x16x32_bf16 v[66:69], v[38:41], v[206:209], v[66:69]
	ds_read_b128 v[34:37], v193 offset:4096
	ds_read_b128 v[38:41], v193 offset:5120
	ds_read_b128 v[114:117], v193 offset:6144
	v_mfma_f32_16x16x32_bf16 v[126:129], v[46:49], v[210:213], v[126:129]
	v_mfma_f32_16x16x32_bf16 v[106:109], v[46:49], v[206:209], v[106:109]
	v_add_co_u32_e64 v48, s[6:7], s68, v42
	v_lshl_add_u64 v[46:47], v[42:43], 0, s[54:55]
	s_nop 0
	v_addc_co_u32_e64 v49, s[6:7], 0, v43, s[6:7]
	v_add_co_u32_e64 v228, s[6:7], s68, v44
	v_lshl_add_u64 v[42:43], v[42:43], 0, s[56:57]
	s_nop 0
	v_addc_co_u32_e64 v229, s[6:7], 0, v45, s[6:7]
	s_waitcnt lgkmcnt(2)
	v_mfma_f32_16x16x32_bf16 v[70:73], v[34:37], v[210:213], v[70:73]
	global_load_dwordx4 v[58:61], v[48:49], off
	global_load_dwordx4 v[62:65], v[46:47], off offset:16
	global_load_dwordx4 v[54:57], v[48:49], off offset:128
	global_load_dwordx4 v[50:53], v[42:43], off offset:16
	s_lshl_b64 s[6:7], s[60:61], 1
	v_mfma_f32_16x16x32_bf16 v[78:81], v[34:37], v[206:209], v[78:81]
	v_lshl_add_u64 v[34:35], v[44:45], 0, s[56:57]
	global_load_dwordx4 v[46:49], v[228:229], off
	global_load_dwordx4 v[42:45], v[226:227], off offset:16
	s_waitcnt lgkmcnt(1)
	v_mfma_f32_16x16x32_bf16 v[218:221], v[38:41], v[210:213], v[86:89]
	s_nop 2
	ds_read_b128 v[86:89], v193 offset:7168
	v_mfma_f32_16x16x32_bf16 v[222:225], v[38:41], v[206:209], v[90:93]
	global_load_dwordx4 v[38:41], v[228:229], off offset:128
	s_nop 0
	global_load_dwordx4 v[34:37], v[34:35], off offset:16
	s_nop 0
	s_waitcnt vmcnt(19)
	ds_write_b128 v164, v[234:237] offset:16384
	s_waitcnt vmcnt(18)
	ds_write_b128 v192, v[238:241] offset:16384
	s_waitcnt lgkmcnt(2)
	v_mfma_f32_16x16x32_bf16 v[194:197], v[86:89], v[210:213], v[194:197]
	s_waitcnt lgkmcnt(0)
	s_barrier
	v_mfma_f32_16x16x32_bf16 v[134:137], v[86:89], v[206:209], v[134:137]
	ds_read_b128 v[86:89], v193 offset:16384
	ds_read_b128 v[90:93], v193 offset:17408
	v_mfma_f32_16x16x32_bf16 v[74:77], v[114:117], v[210:213], v[74:77]
	v_mfma_f32_16x16x32_bf16 v[82:85], v[114:117], v[206:209], v[82:85]
	s_waitcnt lgkmcnt(1)
	v_mfma_f32_16x16x32_bf16 v[130:133], v[86:89], v[122:125], v[94:97]
	v_mfma_f32_16x16x32_bf16 v[114:117], v[86:89], v[198:201], v[98:101]
	s_waitcnt lgkmcnt(0)
	v_mfma_f32_16x16x32_bf16 v[126:129], v[90:93], v[122:125], v[126:129]
	v_mfma_f32_16x16x32_bf16 v[106:109], v[90:93], v[198:201], v[106:109]
	ds_read_b128 v[86:89], v193 offset:18432
	ds_read_b128 v[90:93], v193 offset:19456
	s_waitcnt lgkmcnt(1)
	v_mfma_f32_16x16x32_bf16 v[118:121], v[86:89], v[122:125], v[118:121]
	v_mfma_f32_16x16x32_bf16 v[102:105], v[86:89], v[198:201], v[102:105]
	s_waitcnt lgkmcnt(0)
	v_mfma_f32_16x16x32_bf16 v[86:89], v[90:93], v[198:201], v[66:69]
	s_nop 2
	ds_read_b128 v[66:69], v193 offset:20480
	ds_read_b128 v[98:101], v193 offset:21504
	ds_read_b128 v[202:205], v193 offset:22528
	ds_read_b128 v[206:209], v193 offset:23552
	s_waitcnt lgkmcnt(3)
	v_mfma_f32_16x16x32_bf16 v[94:97], v[66:69], v[122:125], v[70:73]
	s_nop 2
	v_lshl_add_u64 v[70:71], v[168:169], 0, s[6:7]
	v_mfma_f32_16x16x32_bf16 v[78:81], v[66:69], v[198:201], v[78:81]
	v_lshl_add_u64 v[66:67], v[166:167], 0, s[6:7]
	global_load_dwordx4 v[66:69], v[66:67], off
	s_nop 0
	global_load_dwordx4 v[70:73], v[70:71], off
	v_mfma_f32_16x16x32_bf16 v[110:113], v[90:93], v[122:125], v[110:113]
	s_waitcnt vmcnt(11)
	ds_write_b128 v164, v[242:245]
	s_waitcnt vmcnt(10)
	ds_write_b128 v192, v[246:249]
	s_waitcnt lgkmcnt(4)
	v_mfma_f32_16x16x32_bf16 v[90:93], v[98:101], v[122:125], v[218:221]
	s_waitcnt lgkmcnt(0)
	s_barrier
	v_mfma_f32_16x16x32_bf16 v[98:101], v[98:101], v[198:201], v[222:225]
	v_mfma_f32_16x16x32_bf16 v[74:77], v[202:205], v[122:125], v[74:77]
	v_mfma_f32_16x16x32_bf16 v[82:85], v[202:205], v[198:201], v[82:85]
	v_mfma_f32_16x16x32_bf16 v[122:125], v[206:209], v[122:125], v[194:197]
	v_mfma_f32_16x16x32_bf16 v[134:137], v[206:209], v[198:201], v[134:137]
	s_cbranch_vccnz .LBB0_774
	s_lshl_b32 s6, s69, 2
	s_or_b32 s6, s6, s89
	s_ashr_i32 s7, s6, 31
	s_lshl_b64 s[6:7], s[6:7], 9
	s_or_b32 s6, s6, s70
	v_or_b32_e32 v2, s6, v159
	v_mov_b32_e32 v3, s7
	v_lshlrev_b64 v[2:3], 9, v[2:3]
	v_lshlrev_b32_e32 v4, 2, v191
	v_lshl_add_u64 v[2:3], s[12:13], 0, v[2:3]
	v_ashrrev_i32_e32 v5, 31, v4
	v_lshl_add_u64 v[2:3], v[4:5], 1, v[2:3]
	v_cvt_pk_bf16_f32 v4, v130, v131
	v_cvt_pk_bf16_f32 v5, v132, v133
	global_store_dwordx2 v[2:3], v[4:5], off
	v_cvt_pk_bf16_f32 v4, v126, v127
	v_cvt_pk_bf16_f32 v5, v128, v129
	global_store_dwordx2 v[2:3], v[4:5], off offset:32
	v_cvt_pk_bf16_f32 v4, v118, v119
	v_cvt_pk_bf16_f32 v5, v120, v121
	global_store_dwordx2 v[2:3], v[4:5], off offset:64
	v_cvt_pk_bf16_f32 v4, v110, v111
	v_cvt_pk_bf16_f32 v5, v112, v113
	global_store_dwordx2 v[2:3], v[4:5], off offset:96
	v_cvt_pk_bf16_f32 v4, v94, v95
	v_cvt_pk_bf16_f32 v5, v96, v97
	global_store_dwordx2 v[2:3], v[4:5], off offset:128
	v_cvt_pk_bf16_f32 v4, v90, v91
	v_cvt_pk_bf16_f32 v5, v92, v93
	global_store_dwordx2 v[2:3], v[4:5], off offset:160
	v_cvt_pk_bf16_f32 v4, v74, v75
	v_cvt_pk_bf16_f32 v5, v76, v77
	global_store_dwordx2 v[2:3], v[4:5], off offset:192
	v_cvt_pk_bf16_f32 v4, v122, v123
	v_cvt_pk_bf16_f32 v5, v124, v125
	global_store_dwordx2 v[2:3], v[4:5], off offset:224
	v_add_co_u32_e32 v2, vcc, s62, v2
	v_cvt_pk_bf16_f32 v4, v114, v115
	v_cvt_pk_bf16_f32 v5, v116, v117
	v_addc_co_u32_e32 v3, vcc, 0, v3, vcc
	global_store_dwordx2 v[2:3], v[4:5], off
	v_cvt_pk_bf16_f32 v4, v106, v107
	v_cvt_pk_bf16_f32 v5, v108, v109
	global_store_dwordx2 v[2:3], v[4:5], off offset:32
	v_cvt_pk_bf16_f32 v4, v102, v103
	v_cvt_pk_bf16_f32 v5, v104, v105
	global_store_dwordx2 v[2:3], v[4:5], off offset:64
	v_cvt_pk_bf16_f32 v4, v86, v87
	v_cvt_pk_bf16_f32 v5, v88, v89
	global_store_dwordx2 v[2:3], v[4:5], off offset:96
	v_cvt_pk_bf16_f32 v4, v78, v79
	v_cvt_pk_bf16_f32 v5, v80, v81
	global_store_dwordx2 v[2:3], v[4:5], off offset:128
	v_cvt_pk_bf16_f32 v4, v98, v99
	v_cvt_pk_bf16_f32 v5, v100, v101
	global_store_dwordx2 v[2:3], v[4:5], off offset:160
	v_cvt_pk_bf16_f32 v4, v82, v83
	v_cvt_pk_bf16_f32 v5, v84, v85
	s_add_i32 s6, s65, 0xc0
	global_store_dwordx2 v[2:3], v[4:5], off offset:192
	v_cvt_pk_bf16_f32 v4, v134, v135
	v_cvt_pk_bf16_f32 v5, v136, v137
	s_cmpk_gt_i32 s65, 0x13f
	s_mov_b32 s65, s6
	global_store_dwordx2 v[2:3], v[4:5], off offset:224
	s_barrier
	s_cbranch_scc0 .LBB0_773
